# one static s_setprio 1 for waves 4-7 during the neighbourhood-attention phase (reset at phase exit)
# baseline (speedup 1.0000x reference)
.LBB0_1237:
	s_cmp_lt_u32 s81, 4
	s_cbranch_scc1 .Lnatprio_skip
	s_setprio 1

.LBB0_1288:
	s_setprio 0
	s_mov_b32 s63, s89
	v_readlane_b32 s89, v254, 39
	v_readlane_b32 s81, v254, 47
